# static s_setprio 1 for waves 4-7 (younger half) around the Hyena conv main loop, no per-segment flips
# speedup vs baseline: 1.0006x; 1.0006x over previous
; __device__ __forceinline__ void hyena_conv_mfma(const Args& a, int l, int o, unsigned char* sm, const bf16_t* __restrict__ FILT, const u64_t* __restrict__ FSUM,
;                                                 const bf16_t* __restrict__ ZinT, const bf16_t* __restrict__ GT, bf16_t* __restrict__ OutT) {
;     ...
;         const unsigned* kd = (const unsigned*)Kl;
;         const int r16 = lane & 15, kg = lane >> 4;
;         const int n0 = 32 * wn, sb0 = 4 * n0 + 320 * wk;
;         const unsigned sh = ((1 + r16) & 1) * 16;
;         const int xb = 1 + 8 * kg + r16 + 32 * sb0;
;         const int zi0 = M_PAD - (n0 + r16) * 128 + 8 * kg + 32 * sb0;
;         f32x4 acc[8][2];
; #pragma unroll
;         for (int q = 0; q < 8; ++q)
; #pragma unroll
;             for (int cc = 0; cc < 2; ++cc) acc[q][cc] = (f32x4){0.f, 0.f, 0.f, 0.f};
;         {
;         bf16x8 R[10];
; #pragma unroll
;         for (int m = 0; m < 6; ++m) R[m] = ld_kfrag(kd, xb + 16 * m, sh);
;         unsigned ra[5], rb[5];
;         { const int dwa = (xb + 16 * 6) >> 1, dwb = (xb + 16 * 7) >> 1;
; #pragma unroll
;           for (int e = 0; e < 5; ++e) { ra[e] = kd[dwa + e]; rb[e] = kd[dwb + e]; } }
;         bf16x8 zr0 = *(const bf16x8*)(zp + zpad(zi0)), zr1 = *(const bf16x8*)(zp + zpad(zi0 - 16 * 128));
;         const int wks = __builtin_amdgcn_readfirstlane(wk);
.LBB0_407:
	s_or_b64 exec, exec, s[2:3]
	s_waitcnt lgkmcnt(0)
	s_barrier
	s_waitcnt vmcnt(0)
	ds_read2_b32 v[4:5], v167 offset0:3 offset1:4
	ds_read2_b32 v[6:7], v167 offset0:32 offset1:33
	ds_read2_b32 v[8:9], v167 offset0:1 offset1:2
	ds_read2_b32 v[10:11], v167 offset1:1
	v_readfirstlane_b32 s3, v152
	s_waitcnt lgkmcnt(3)
	v_alignbit_b32 v73, v5, v4, v3
	v_mov_b32_e32 v64, v65
	s_waitcnt lgkmcnt(1)
	v_alignbit_b32 v72, v4, v9, v2
	s_waitcnt lgkmcnt(0)
	v_alignbit_b32 v71, v9, v11, v1
	v_alignbit_b32 v70, v8, v10, v0
	ds_read2_b32 v[4:5], v168 offset0:3 offset1:4
	ds_read2_b32 v[8:9], v168 offset1:1
	ds_read2_b32 v[10:11], v168 offset0:1 offset1:2
	ds_read2_b32 v[12:13], v169 offset1:1
	ds_read2_b32 v[14:15], v169 offset0:1 offset1:2
	ds_read2_b32 v[16:17], v169 offset0:3 offset1:4
	s_waitcnt lgkmcnt(5)
	v_alignbit_b32 v77, v5, v4, v3
	s_waitcnt lgkmcnt(3)
	v_alignbit_b32 v76, v4, v11, v2
	ds_read2_b32 v[4:5], v167 offset0:33 offset1:34
	ds_read2_b32 v[18:19], v167 offset0:35 offset1:36
	v_alignbit_b32 v75, v11, v9, v1
	v_alignbit_b32 v74, v10, v8, v0
	ds_read2_b32 v[8:9], v170 offset1:1
	ds_read2_b32 v[10:11], v170 offset0:1 offset1:2
	ds_read2_b32 v[20:21], v170 offset0:3 offset1:4
	s_waitcnt lgkmcnt(6)
	v_alignbit_b32 v79, v15, v13, v1
	v_alignbit_b32 v78, v14, v12, v0
	ds_read2_b32 v[12:13], v172 offset1:1
	s_waitcnt lgkmcnt(2)
	v_alignbit_b32 v83, v11, v9, v1
	s_waitcnt lgkmcnt(1)
	v_alignbit_b32 v84, v20, v11, v2
	v_alignbit_b32 v82, v10, v8, v0
	ds_read2_b32 v[8:9], v172 offset0:1 offset1:2
	ds_read2_b32 v[10:11], v172 offset0:3 offset1:4
	ds_read_b32 v94, v155
	ds_read_b32 v124, v156
	ds_read2_b32 v[96:97], v155 offset0:1 offset1:2
	ds_read2_b32 v[98:99], v155 offset0:3 offset1:4
	ds_read2_b32 v[100:101], v156 offset0:1 offset1:2
	ds_read2_b32 v[122:123], v156 offset0:3 offset1:4
	ds_read_b128 v[114:117], v157 offset:8192
	ds_read_b128 v[110:113], v158 offset:8192
	v_alignbit_b32 v81, v17, v16, v3
	v_alignbit_b32 v80, v16, v15, v2
	v_alignbit_b32 v85, v21, v20, v3
	v_alignbit_b32 v89, v19, v18, v3
	v_alignbit_b32 v88, v18, v5, v2
	v_alignbit_b32 v87, v5, v7, v1
	v_alignbit_b32 v86, v4, v6, v0
	s_waitcnt lgkmcnt(8)
	v_alignbit_b32 v93, v11, v10, v3
	v_alignbit_b32 v92, v10, v9, v2
	v_alignbit_b32 v91, v9, v13, v1
	v_alignbit_b32 v90, v8, v12, v0
	s_cmp_eq_u32 s3, 1
	s_cbranch_scc0 .Lconv_noprio
	s_setprio 1
.Lconv_noprio:
	s_cmp_lg_u32 s3, 1
	v_mov_b32_e32 v66, v65
	v_mov_b32_e32 v67, v65
	v_mov_b64_e32 v[4:5], v[64:65]
	v_mov_b64_e32 v[8:9], v[64:65]
	v_mov_b64_e32 v[12:13], v[64:65]
	v_mov_b64_e32 v[16:17], v[64:65]
	v_mov_b64_e32 v[20:21], v[64:65]
	v_mov_b64_e32 v[24:25], v[64:65]
	v_mov_b64_e32 v[28:29], v[64:65]
	v_mov_b64_e32 v[32:33], v[64:65]
	v_mov_b64_e32 v[36:37], v[64:65]
	v_mov_b64_e32 v[40:41], v[64:65]
	v_mov_b64_e32 v[44:45], v[64:65]
	v_mov_b64_e32 v[48:49], v[64:65]
	v_mov_b64_e32 v[52:53], v[64:65]
	v_mov_b64_e32 v[56:57], v[64:65]
	v_mov_b64_e32 v[60:61], v[64:65]
	s_cselect_b64 s[56:57], -1, 0
	s_cmp_lg_u32 s3, 0
	v_mov_b64_e32 v[6:7], v[66:67]
	v_mov_b64_e32 v[10:11], v[66:67]
	v_mov_b64_e32 v[14:15], v[66:67]
	v_mov_b64_e32 v[18:19], v[66:67]
	v_mov_b64_e32 v[22:23], v[66:67]
	v_mov_b64_e32 v[26:27], v[66:67]
	v_mov_b64_e32 v[30:31], v[66:67]
	v_mov_b64_e32 v[34:35], v[66:67]
	v_mov_b64_e32 v[38:39], v[66:67]
	v_mov_b64_e32 v[42:43], v[66:67]
	v_mov_b64_e32 v[46:47], v[66:67]
	v_mov_b64_e32 v[50:51], v[66:67]
	v_mov_b64_e32 v[54:55], v[66:67]
	v_mov_b64_e32 v[58:59], v[66:67]
	v_mov_b64_e32 v[62:63], v[66:67]
	v_mov_b64_e32 v[68:69], v[66:67]
	s_mov_b32 s2, 0
	s_cselect_b64 s[58:59], -1, 0
	v_mov_b32_e32 v185, v178
	v_mov_b64_e32 v[66:67], v[64:65]
	s_mov_b32 s3, 0
	v_ashrrev_i32_e32 v201, 7, v179
	v_lshl_add_u32 v185, v201, 4, v185
	v_lshlrev_b32_e32 v201, 1, v180
	v_add_u32_e32 v201, 0x102, v201
	v_and_b32_e32 v201, -4, v201
	s_branch .LBB0_409

; __device__ __forceinline__ void hyena_conv_mfma(const Args& a, int l, int o, unsigned char* sm, const bf16_t* __restrict__ FILT, const u64_t* __restrict__ FSUM,
;                                                 const bf16_t* __restrict__ ZinT, const bf16_t* __restrict__ GT, bf16_t* __restrict__ OutT) {
;     ...
;                 __builtin_amdgcn_sched_barrier(0);
;             }
;         }
;         }
;         __syncthreads();
;         float* yb = (float*)(sm + M_K);
;         if (wk == 0) {
; #pragma unroll
;             for (int q = 0; q < 8; ++q)
; #pragma unroll
;                 for (int cc = 0; cc < 2; ++cc)
; #pragma unroll
;                     for (int e = 0; e < 4; ++e) yb[(n0 + 16 * cc + r16) * 129 + 16 * q + 4 * kg + e] = acc[q][cc][e];
;         }
.LBB0_429:
	s_setprio 0
	v_add_u32_e32 v84, 0x2040, v173
	v_add_u32_e32 v83, 0x2048, v173
	v_add_u32_e32 v82, 0x2080, v173
	v_add_u32_e32 v81, 0x2088, v173
	v_add_u32_e32 v80, 0x20c0, v173
	v_add_u32_e32 v79, 0x20c8, v173
	v_add_u32_e32 v78, 0x2100, v173
	v_add_u32_e32 v77, 0x2108, v173
	v_add_u32_e32 v76, 0x2140, v173
	v_add_u32_e32 v75, 0x2148, v173
	v_add_u32_e32 v74, 0x2180, v173
	v_add_u32_e32 v73, 0x2188, v173
	v_add_u32_e32 v72, 0x21c0, v173
	v_add_u32_e32 v71, 0x21c8, v173
	v_add_u32_e32 v70, 0x2200, v173
	v_add_u32_e32 v64, 0x2208, v173
	s_waitcnt lgkmcnt(0)
	s_barrier
	s_mov_b64 s[2:3], exec
	v_readlane_b32 s26, v244, 0
	v_readlane_b32 s27, v244, 1
	s_and_b64 s[26:27], s[2:3], s[26:27]
	s_mov_b64 exec, s[26:27]
	s_cbranch_execz .LBB0_431
	ds_write2_b32 v173, v66, v67 offset1:1
	ds_write2_b32 v173, v68, v69 offset0:2 offset1:3
	ds_write2_b32 v84, v60, v61 offset1:1
	ds_write2_b32 v83, v62, v63 offset1:1
	ds_write2_b32 v173, v56, v57 offset0:16 offset1:17
	ds_write2_b32 v173, v58, v59 offset0:18 offset1:19
	ds_write2_b32 v82, v52, v53 offset1:1
	ds_write2_b32 v81, v54, v55 offset1:1
	ds_write2_b32 v173, v48, v49 offset0:32 offset1:33
	ds_write2_b32 v173, v50, v51 offset0:34 offset1:35
	ds_write2_b32 v80, v44, v45 offset1:1
	ds_write2_b32 v79, v46, v47 offset1:1
	ds_write2_b32 v173, v40, v41 offset0:48 offset1:49
	ds_write2_b32 v173, v42, v43 offset0:50 offset1:51
	ds_write2_b32 v78, v36, v37 offset1:1
	ds_write2_b32 v77, v38, v39 offset1:1
	ds_write2_b32 v173, v32, v33 offset0:64 offset1:65
	ds_write2_b32 v173, v34, v35 offset0:66 offset1:67
	ds_write2_b32 v76, v28, v29 offset1:1
	ds_write2_b32 v75, v30, v31 offset1:1
	ds_write2_b32 v173, v24, v25 offset0:80 offset1:81
	ds_write2_b32 v173, v26, v27 offset0:82 offset1:83
	ds_write2_b32 v74, v20, v21 offset1:1
	ds_write2_b32 v73, v22, v23 offset1:1
	ds_write2_b32 v173, v16, v17 offset0:96 offset1:97
	ds_write2_b32 v173, v18, v19 offset0:98 offset1:99
	ds_write2_b32 v72, v12, v13 offset1:1
	ds_write2_b32 v71, v14, v15 offset1:1
	ds_write2_b32 v173, v8, v9 offset0:112 offset1:113
	ds_write2_b32 v173, v10, v11 offset0:114 offset1:115
	ds_write2_b32 v70, v4, v5 offset1:1
	ds_write2_b32 v64, v6, v7 offset1:1
